# v5 plus: per-head mLSTM weight image loaded with all five loads of a thread in flight (P3 and P4 copies)
# speedup vs baseline: 1.0093x; 1.0093x over previous
; #define LAS __attribute__((address_space(3)))
; __device__ __forceinline__ void ml_load_weights(LAS float* WL, const MixBufs& B, int h, int tid) {
;     for (int i = tid; i < WL_FLOATS; i += 512) { float v;
;         if (i < WL_CB) v = B.conv_w[(i >> 7) * 512 + h * 128 + (i & 127)];
;         else if (i < WL_WQ) v = B.conv_b[h * 128 + i - WL_CB];
;         else if (i < WL_WK) v = B.w_q[h * 512 + i - WL_WQ];
;         else if (i < WL_WV) v = B.w_k[h * 512 + i - WL_WK] * DHS;
;         else v = B.w_v[h * 512 + i - WL_WV];
;         WL[i] = v; }
; }
; template <int PH> __device__ __forceinline__ void run_phase(Frame& F, const Args& args) {
;     ...
;             if (F.G == 256) { const int l = F.vcu & 31, xc = F.vcu >> 5;
;                 if (l < 24) { const int ty = l >= 12, r = xc * 12 + (l - 12 * ty), b = r / 12, h = (r % 12) / 3, sg = r % 3;
;                     if (ty == 0) mix::gla_unit<false>(F.lds, MB, b, h, sg, F.tid); else mix::ml_loc_unit(F.lds, MB, b, h, sg, F.tid); } }
.LBB0_452:
	s_andn2_b64 vcc, exec, s[2:3]
	s_cbranch_vccnz .LBB0_541
	s_and_b32 s2, s84, 31
	s_cmp_gt_u32 s2, 23
	s_cbranch_scc1 .LBB0_541
	s_ashr_i32 s3, s84, 5
	s_cmp_lt_u32 s2, 12
	s_mul_i32 s3, s3, 12
	s_cselect_b32 s4, 0, -12
	s_add_i32 s3, s3, s2
	s_add_i32 s3, s3, s4
	s_mul_hi_i32 s4, s3, 0x2aaaaaab
	s_lshr_b32 s5, s4, 31
	s_ashr_i32 s4, s4, 1
	s_add_i32 s8, s4, s5
	s_mul_i32 s4, s8, 12
	s_sub_i32 s4, s3, s4
	s_mulk_i32 s4, 0x56
	s_bfe_u32 s5, s4, 0x1000f
	s_bfe_u32 s25, s4, 0x80008
	s_mul_hi_i32 s4, s3, 0x55555556
	s_add_i32 s25, s25, s5
	s_lshr_b32 s5, s4, 31
	s_add_i32 s4, s4, s5
	s_mul_i32 s4, s4, 3
	s_sub_i32 s24, s3, s4
	s_cmp_gt_u32 s2, 11
	s_sext_i32_i8 s22, s25
	s_cbranch_scc0 .LBB0_474
	v_mov_b32_e32 v18, v0
	s_movk_i32 s2, 0x880
	s_nop 0
	v_readfirstlane_b32 s23, v18
	v_cmp_gt_i32_e32 vcc, s2, v18
	v_lshlrev_b32_e32 v20, 2, v18
	s_and_saveexec_b64 s[2:3], vcc
	v_readlane_b32 s28, v240, 5
	v_readlane_b32 s29, v240, 6
	s_cbranch_execz .LBB0_475
	s_lshl_b32 s18, s22, 7
	v_and_b32_e32 v1, 0x7f, v18
	s_lshl_b32 s9, s22, 9
	v_or_b32_e32 v1, s18, v1
	s_mov_b64 s[4:5], 0
	s_movk_i32 s19, 0x67f
	v_mov_b32_e32 v3, 0
	v_mov_b32_e32 v6, v20
	v_mov_b32_e32 v7, v18
	v_readlane_b32 s36, v241, 2
	v_readlane_b32 s37, v241, 3
	v_readlane_b32 s38, v241, 4
	v_readlane_b32 s39, v241, 5
	v_readlane_b32 s40, v241, 6
	v_readlane_b32 s41, v241, 7
	s_movk_i32 s14, 0x80
	v_cmp_gt_u32_e64 s[6:7], s14, v18
	v_and_b32_e32 v200, 0xfe00, v20
	v_or_b32_e32 v200, v200, v1
	v_mov_b32_e32 v201, 0
	v_lshl_add_u64 v[200:201], v[200:201], 2, s[64:65]
	global_load_dword v210, v[200:201], off
	v_mov_b32_e32 v202, 0xffffff80
	v_mov_b32_e32 v203, 0x180
	v_cndmask_b32_e64 v202, v202, v203, s[6:7]
	v_add3_u32 v202, v18, s9, v202
	v_mov_b32_e32 v203, 0
	v_lshl_add_u64 v[204:205], v[202:203], 2, s[36:37]
	v_lshl_add_u64 v[206:207], v[202:203], 2, s[38:39]
	v_lshl_add_u64 v[208:209], v[202:203], 2, s[40:41]
	v_add_u32_e32 v212, s18, v18
	v_mov_b32_e32 v213, 0
	v_lshl_add_u64 v[212:213], v[212:213], 2, s[66:67]
	v_cndmask_b32_e64 v214, v204, v212, s[6:7]
	v_cndmask_b32_e64 v215, v205, v213, s[6:7]
	global_load_dword v211, v[214:215], off
	v_cndmask_b32_e64 v214, v206, v204, s[6:7]
	v_cndmask_b32_e64 v215, v207, v205, s[6:7]
	global_load_dword v212, v[214:215], off
	v_cndmask_b32_e64 v214, v208, v206, s[6:7]
	v_cndmask_b32_e64 v215, v209, v207, s[6:7]
	global_load_dword v213, v[214:215], off
	s_and_saveexec_b64 s[10:11], s[6:7]
	global_load_dword v216, v[208:209], off
	s_mov_b64 exec, s[10:11]
	s_waitcnt vmcnt(0)
	v_mul_f32_e32 v214, 0x3db504f3, v212
	v_mul_f32_e32 v215, 0x3db504f3, v213
	v_cndmask_b32_e64 v212, v214, v212, s[6:7]
	v_cndmask_b32_e64 v213, v213, v215, s[6:7]
	ds_write_b32 v20, v210 offset:35328
	ds_write_b32 v20, v211 offset:37376
	ds_write_b32 v20, v212 offset:39424
	ds_write_b32 v20, v213 offset:41472
	s_and_saveexec_b64 s[10:11], s[6:7]
	ds_write_b32 v20, v216 offset:43520
	s_mov_b64 exec, s[10:11]
	s_branch .LBB0_475

; #define LAS __attribute__((address_space(3)))
; __device__ __forceinline__ void ml_load_weights(LAS float* WL, const MixBufs& B, int h, int tid) {
;     for (int i = tid; i < WL_FLOATS; i += 512) { float v;
;         if (i < WL_CB) v = B.conv_w[(i >> 7) * 512 + h * 128 + (i & 127)];
;         else if (i < WL_WQ) v = B.conv_b[h * 128 + i - WL_CB];
;         else if (i < WL_WK) v = B.w_q[h * 512 + i - WL_WQ];
;         else if (i < WL_WV) v = B.w_k[h * 512 + i - WL_WK] * DHS;
;         else v = B.w_v[h * 512 + i - WL_WV];
;         WL[i] = v; }
; }
.LBB0_601:
	s_or_b64 exec, exec, s[2:3]
	s_movk_i32 s2, 0x880
	v_cmp_gt_i32_e32 vcc, s2, v166
	s_and_saveexec_b64 s[2:3], vcc
	s_cbranch_execz .LBB0_621
	s_lshr_b32 s4, s72, 2
	s_and_b32 s4, s4, 3
	v_and_b32_e32 v2, 0x7f, v166
	s_lshl_b32 s21, s4, 9
	s_lshl_b32 s22, s4, 7
	v_lshl_or_b32 v4, s8, 7, v2
	s_mov_b64 s[4:5], 0
	v_mov_b32_e32 v5, v187
	v_mov_b32_e32 v6, v166
	v_readlane_b32 s36, v241, 2
	v_readlane_b32 s37, v241, 3
	v_readlane_b32 s38, v241, 4
	v_readlane_b32 s39, v241, 5
	v_readlane_b32 s40, v241, 6
	v_readlane_b32 s41, v241, 7
	s_movk_i32 s16, 0x80
	v_cmp_gt_u32_e64 s[12:13], s16, v166
	v_and_b32_e32 v200, 0xfe00, v187
	v_or_b32_e32 v200, v200, v4
	v_mov_b32_e32 v201, 0
	v_lshl_add_u64 v[200:201], v[200:201], 2, s[64:65]
	global_load_dword v210, v[200:201], off
	v_mov_b32_e32 v202, 0xffffff80
	v_mov_b32_e32 v203, 0x180
	v_cndmask_b32_e64 v202, v202, v203, s[12:13]
	v_add3_u32 v202, v166, s21, v202
	v_mov_b32_e32 v203, 0
	v_lshl_add_u64 v[204:205], v[202:203], 2, s[36:37]
	v_lshl_add_u64 v[206:207], v[202:203], 2, s[38:39]
	v_lshl_add_u64 v[208:209], v[202:203], 2, s[40:41]
	v_add_u32_e32 v212, s22, v166
	v_mov_b32_e32 v213, 0
	v_lshl_add_u64 v[212:213], v[212:213], 2, s[66:67]
	v_cndmask_b32_e64 v214, v204, v212, s[12:13]
	v_cndmask_b32_e64 v215, v205, v213, s[12:13]
	global_load_dword v211, v[214:215], off
	v_cndmask_b32_e64 v214, v206, v204, s[12:13]
	v_cndmask_b32_e64 v215, v207, v205, s[12:13]
	global_load_dword v212, v[214:215], off
	v_cndmask_b32_e64 v214, v208, v206, s[12:13]
	v_cndmask_b32_e64 v215, v209, v207, s[12:13]
	global_load_dword v213, v[214:215], off
	s_and_saveexec_b64 s[14:15], s[12:13]
	global_load_dword v216, v[208:209], off
	s_mov_b64 exec, s[14:15]
	s_waitcnt vmcnt(0)
	v_mul_f32_e32 v214, 0x3db504f3, v212
	v_mul_f32_e32 v215, 0x3db504f3, v213
	v_cndmask_b32_e64 v212, v214, v212, s[12:13]
	v_cndmask_b32_e64 v213, v213, v215, s[12:13]
	v_add_u32_e32 v200, 0x22c00, v187
	ds_write_b32 v200, v210
	ds_write_b32 v200, v211 offset:2048
	ds_write_b32 v200, v212 offset:4096
	ds_write_b32 v200, v213 offset:6144
	s_and_saveexec_b64 s[14:15], s[12:13]
	ds_write_b32 v200, v216 offset:8192
	s_mov_b64 exec, s[14:15]
	s_branch .LBB0_621
